# post-projection row loop: after a row's loads land, touch the next row's lines (loads into unused registers) so the next iteration hits cache, on top of v32
# speedup vs baseline: 1.0051x; 1.0051x over previous
.LBB0_334:
	s_or_b64 exec, exec, s[0:1]
	v_lshlrev_b32_e32 v130, 4, v130
	v_ashrrev_i32_e32 v131, 31, v130
	v_lshl_add_u64 v[138:139], v[130:131], 2, v[150:151]
	s_mov_b64 s[0:1], 0x2000
	v_lshl_add_u64 v[140:141], v[138:139], 0, s[0:1]
	s_movk_i32 s0, 0x2000
	global_load_dwordx4 v[134:137], v[138:139], off
	global_load_dwordx4 v[130:133], v[138:139], off offset:16
	v_add_co_u32_e32 v138, vcc, s0, v138
	s_waitcnt vmcnt(5)
	v_lshlrev_b32_e32 v164, 16, v146
	v_addc_co_u32_e32 v139, vcc, 0, v139, vcc
	global_load_dwordx4 v[142:145], v[138:139], off
	s_nop 0
	global_load_dwordx4 v[138:141], v[140:141], off offset:16
	v_and_b32_e32 v165, 0xffff0000, v146
	v_lshlrev_b32_e32 v160, 16, v147
	v_and_b32_e32 v161, 0xffff0000, v147
	v_pk_mul_f32 v[146:147], v[164:165], v[164:165]
	v_pk_mul_f32 v[162:163], v[160:161], v[160:161]
	v_add_f32_e32 v146, v146, v147
	v_lshlrev_b32_e32 v158, 16, v148
	v_and_b32_e32 v159, 0xffff0000, v148
	v_add_f32_e32 v146, v162, v146
	v_lshlrev_b32_e32 v154, 16, v149
	v_and_b32_e32 v155, 0xffff0000, v149
	v_pk_mul_f32 v[148:149], v[158:159], v[158:159]
	v_add_f32_e32 v146, v163, v146
	v_add_f32_e32 v146, v148, v146
	v_pk_mul_f32 v[156:157], v[154:155], v[154:155]
	v_add_f32_e32 v146, v149, v146
	v_add_f32_e32 v146, v156, v146
	v_add_f32_e32 v146, v157, v146
	ds_bpermute_b32 v147, v176, v146
	s_waitcnt lgkmcnt(0)
	v_add_f32_e32 v146, v146, v147
	ds_bpermute_b32 v147, v177, v146
	s_waitcnt lgkmcnt(0)
	v_add_f32_e32 v146, v146, v147
	ds_bpermute_b32 v147, v178, v146
	s_waitcnt lgkmcnt(0)
	v_add_f32_e32 v146, v146, v147
	v_fmamk_f32 v146, v146, 0x3c800000, v199
	v_cmp_gt_f32_e32 vcc, s21, v146
	v_mul_f32_e32 v147, 0x4f800000, v146
	s_nop 0
	v_cndmask_b32_e32 v146, v146, v147, vcc
	v_sqrt_f32_e32 v147, v146
	s_nop 0
	v_add_u32_e32 v148, -1, v147
	v_fma_f32 v149, -v148, v147, v146
	v_cmp_ge_f32_e64 s[50:51], 0, v149
	v_add_u32_e32 v149, 1, v147
	s_nop 0
	v_cndmask_b32_e64 v148, v147, v148, s[50:51]
	v_fma_f32 v147, -v149, v147, v146
	v_cmp_lt_f32_e64 s[50:51], 0, v147
	s_nop 1
	v_cndmask_b32_e64 v147, v148, v149, s[50:51]
	v_mul_f32_e32 v148, 0x37800000, v147
	v_cndmask_b32_e32 v147, v147, v148, vcc
	v_cmp_class_f32_e32 vcc, v146, v200
	s_nop 1
	v_cndmask_b32_e32 v146, v147, v146, vcc
	v_div_scale_f32 v147, s[0:1], v146, v146, 1.0
	v_rcp_f32_e32 v148, v147
	s_nop 0
	v_fma_f32 v149, -v147, v148, 1.0
	v_fmac_f32_e32 v148, v149, v148
	v_div_scale_f32 v149, vcc, 1.0, v146, 1.0
	v_mul_f32_e32 v156, v149, v148
	v_fma_f32 v157, -v147, v156, v149
	v_fmac_f32_e32 v156, v157, v148
	v_fma_f32 v147, -v147, v156, v149
	v_div_fmas_f32 v147, v147, v148, v156
	v_div_fixup_f32 v146, v147, v146, 1.0
	v_pk_mul_f32 v[148:149], v[146:147], v[164:165] op_sel_hi:[0,1]
	v_pk_mul_f32 v[148:149], v[14:15], v[148:149]
	v_pk_mul_f32 v[156:157], v[146:147], v[160:161] op_sel_hi:[0,1]
	v_pk_mul_f32 v[158:159], v[146:147], v[158:159] op_sel_hi:[0,1]
	v_pk_mul_f32 v[146:147], v[146:147], v[154:155] op_sel_hi:[0,1]
	ds_bpermute_b32 v154, v177, v148
	ds_bpermute_b32 v155, v177, v149
	v_pk_mul_f32 v[156:157], v[16:17], v[156:157]
	v_pk_mul_f32 v[158:159], v[10:11], v[158:159]
	v_pk_mul_f32 v[146:147], v[12:13], v[146:147]
	s_waitcnt vmcnt(1) lgkmcnt(0)
	v_pk_mul_f32 v[154:155], v[142:143], v[154:155]
	s_nop 0
	v_cndmask_b32_e64 v155, v155, -v155, s[44:45]
	v_cndmask_b32_e64 v154, v154, -v154, s[44:45]
	v_pk_fma_f32 v[148:149], v[134:135], v[148:149], v[154:155]
	ds_bpermute_b32 v154, v177, v156
	ds_bpermute_b32 v155, v177, v157
	v_pk_mul_f32 v[148:149], v[148:149], s[20:21] op_sel_hi:[1,0]
	s_waitcnt lgkmcnt(0)
	v_pk_mul_f32 v[154:155], v[144:145], v[154:155]
	s_nop 0
	v_cndmask_b32_e64 v155, v155, -v155, s[44:45]
	v_cndmask_b32_e64 v154, v154, -v154, s[44:45]
	v_pk_fma_f32 v[154:155], v[136:137], v[156:157], v[154:155]
	ds_bpermute_b32 v156, v177, v158
	ds_bpermute_b32 v157, v177, v159
	v_pk_mul_f32 v[154:155], v[154:155], s[20:21] op_sel_hi:[1,0]
	s_waitcnt vmcnt(0) lgkmcnt(0)
	s_mov_b64 s[0:1], 0xc302000
	v_lshl_add_u64 v[192:193], s[16:17], 0, v[0:1]
	s_nop 0
	v_lshl_add_u64 v[192:193], v[192:193], 0, s[0:1]
	global_load_dwordx4 v[182:185], v[192:193], off offset:-3584
	global_load_dwordx4 v[182:185], v[192:193], off offset:-512
	global_load_dwordx4 v[182:185], v[192:193], off offset:512
	global_load_dwordx4 v[182:185], v[192:193], off offset:2048
	global_load_dwordx4 v[182:185], v[192:193], off offset:3072
	v_pk_mul_f32 v[156:157], v[138:139], v[156:157]
	s_nop 0
	v_cndmask_b32_e64 v157, v157, -v157, s[44:45]
	v_cndmask_b32_e64 v156, v156, -v156, s[44:45]
	v_pk_fma_f32 v[156:157], v[130:131], v[158:159], v[156:157]
	ds_bpermute_b32 v158, v177, v146
	ds_bpermute_b32 v159, v177, v147
	v_pk_mul_f32 v[156:157], v[156:157], s[20:21] op_sel_hi:[1,0]
	s_waitcnt lgkmcnt(0)
	v_pk_mul_f32 v[158:159], v[140:141], v[158:159]
	s_nop 0
	v_cndmask_b32_e64 v159, v159, -v159, s[44:45]
	v_cndmask_b32_e64 v158, v158, -v158, s[44:45]
	v_pk_fma_f32 v[146:147], v[132:133], v[146:147], v[158:159]
	s_nop 0
	v_pk_mul_f32 v[158:159], v[146:147], s[20:21] op_sel_hi:[1,0]
	v_cvt_pk_bf16_f32 v146, v148, v149
	v_cvt_pk_bf16_f32 v147, v154, v155
	v_cvt_pk_bf16_f32 v148, v156, v157
	v_cvt_pk_bf16_f32 v149, v158, v159
	v_lshl_add_u64 v[154:155], s[10:11], 0, v[0:1]
	v_lshlrev_b32_e32 v156, 16, v126
	v_and_b32_e32 v157, 0xffff0000, v126
	global_store_dwordx4 v[154:155], v[146:149], off
	v_lshlrev_b32_e32 v154, 16, v127
	v_and_b32_e32 v155, 0xffff0000, v127
	v_pk_mul_f32 v[164:165], v[156:157], v[156:157]
	v_pk_mul_f32 v[158:159], v[154:155], v[154:155]
	v_add_f32_e32 v164, v164, v165
	v_lshlrev_b32_e32 v148, 16, v128
	v_and_b32_e32 v149, 0xffff0000, v128
	v_add_f32_e32 v158, v158, v164
	v_pk_mul_f32 v[160:161], v[148:149], v[148:149]
	v_add_f32_e32 v158, v159, v158
	v_lshlrev_b32_e32 v146, 16, v129
	v_and_b32_e32 v147, 0xffff0000, v129
	v_add_f32_e32 v158, v160, v158
	v_pk_mul_f32 v[162:163], v[146:147], v[146:147]
	v_add_f32_e32 v158, v161, v158
	v_add_f32_e32 v158, v162, v158
	v_add_f32_e32 v158, v163, v158
	ds_bpermute_b32 v159, v176, v158
	s_waitcnt lgkmcnt(0)
	v_add_f32_e32 v158, v158, v159
	ds_bpermute_b32 v159, v177, v158
	s_waitcnt lgkmcnt(0)
	v_add_f32_e32 v158, v158, v159
	ds_bpermute_b32 v159, v178, v158
	s_waitcnt lgkmcnt(0)
	v_add_f32_e32 v158, v158, v159
	v_fmamk_f32 v158, v158, 0x3c800000, v199
	v_cmp_gt_f32_e32 vcc, s21, v158
	v_mul_f32_e32 v159, 0x4f800000, v158
	s_nop 0
	v_cndmask_b32_e32 v158, v158, v159, vcc
	v_sqrt_f32_e32 v159, v158
	s_nop 0
	v_add_u32_e32 v160, -1, v159
	v_fma_f32 v161, -v160, v159, v158
	v_cmp_ge_f32_e64 s[50:51], 0, v161
	v_add_u32_e32 v161, 1, v159
	s_nop 0
	v_cndmask_b32_e64 v160, v159, v160, s[50:51]
	v_fma_f32 v159, -v161, v159, v158
	v_cmp_lt_f32_e64 s[50:51], 0, v159
	s_nop 1
	v_cndmask_b32_e64 v159, v160, v161, s[50:51]
	v_mul_f32_e32 v160, 0x37800000, v159
	v_cndmask_b32_e32 v159, v159, v160, vcc
	v_cmp_class_f32_e32 vcc, v158, v200
	s_nop 1
	v_cndmask_b32_e32 v158, v159, v158, vcc
	v_div_scale_f32 v159, s[0:1], v158, v158, 1.0
	v_rcp_f32_e32 v160, v159
	s_nop 0
	v_fma_f32 v161, -v159, v160, 1.0
	v_fmac_f32_e32 v160, v161, v160
	v_div_scale_f32 v161, vcc, 1.0, v158, 1.0
	v_mul_f32_e32 v162, v161, v160
	v_fma_f32 v163, -v159, v162, v161
	v_fmac_f32_e32 v162, v163, v160
	v_fma_f32 v159, -v159, v162, v161
	v_div_fmas_f32 v159, v159, v160, v162
	v_div_fixup_f32 v158, v159, v158, 1.0
	v_pk_mul_f32 v[160:161], v[158:159], v[156:157] op_sel_hi:[0,1]
	v_pk_mul_f32 v[164:165], v[22:23], v[160:161]
	v_pk_mul_f32 v[160:161], v[158:159], v[154:155] op_sel_hi:[0,1]
	v_pk_mul_f32 v[162:163], v[24:25], v[160:161]
	v_pk_mul_f32 v[160:161], v[158:159], v[148:149] op_sel_hi:[0,1]
	v_pk_mul_f32 v[158:159], v[158:159], v[146:147] op_sel_hi:[0,1]
	v_pk_mul_f32 v[160:161], v[18:19], v[160:161]
	v_pk_mul_f32 v[158:159], v[20:21], v[158:159]
	ds_bpermute_b32 v172, v177, v164
	ds_bpermute_b32 v173, v177, v165
	ds_bpermute_b32 v170, v177, v162
	ds_bpermute_b32 v171, v177, v163
	ds_bpermute_b32 v168, v177, v160
	ds_bpermute_b32 v169, v177, v161
	ds_bpermute_b32 v166, v177, v158
	ds_bpermute_b32 v167, v177, v159
	s_and_saveexec_b64 s[0:1], s[46:47]
	s_xor_b64 s[0:1], exec, s[0:1]
	s_cbranch_execz .LBB0_338
	s_and_saveexec_b64 s[22:23], s[48:49]
	s_cbranch_execz .LBB0_337
	v_lshl_add_u64 v[130:131], s[4:5], 0, v[0:1]
	v_add_co_u32_e32 v130, vcc, 0x1326f000, v130
	s_nop 1
	v_addc_co_u32_e32 v131, vcc, 0, v131, vcc
	global_store_dwordx4 v[130:131], v[126:129], off offset:3840
